# window-branch accumulator-init broadcast with 64-bit moves plus gate epilogue address constants
# speedup vs baseline: 1.0025x; 1.0025x over previous
; #define LAS __attribute__((address_space(3)))
; template <int MODE, bool FAST, bool DEFER>
; __device__ __forceinline__ void attn_tile(AttnState& st, const LAS bf16_t* Ks, const LAS bf16_t* Vt, int jb, int tq, bool mybit, int fr, int fq, float (&imp)[16], float& prev_t3, bf16x8 (&pfo)[2][2]) {
;     ...
;     for (int ct = 0; ct < 2; ++ct) { const float nb_ = !FAST ? 0.f : ((MODE == M_SLC && !mybit) ? -1e30f : (st.m[ct] < -1e29f ? 0.f : -st.m[ct])); zinit[ct] = (f32x4){nb_, nb_, nb_, nb_}; }
; #pragma unroll
;     for (int sb = 0; sb < 4; ++sb) {
;         const bf16x8 k0 = *(const LAS bf16x8*)(Ks + (sb * 16 + fr) * KSTR + fq * 8);
;         const bf16x8 k1 = *(const LAS bf16x8*)(Ks + (sb * 16 + fr) * KSTR + 32 + fq * 8);
; #pragma unroll
;         for (int ct = 0; ct < 2; ++ct) {
;             f32x4 z = zinit[ct];
;             z = __builtin_amdgcn_mfma_f32_16x16x32_bf16(k0, st.qf[ct][0], z, 0, 0, 0);
;             z = __builtin_amdgcn_mfma_f32_16x16x32_bf16(k1, st.qf[ct][1], z, 0, 0, 0);
;             s[ct][sb] = ISCMP ? z * ATT_QS : z;
;         }
;     }
;     ...
;     if (FAST) {
;         float tz[2]; bool nd[2]; bool un[2];
; #pragma unroll
;         for (int ct = 0; ct < 2; ++ct) {
;             float t = -1e30f;
; #pragma unroll
;             for (int sb = 0; sb < 4; ++sb)
; #pragma unroll
;                 for (int j = 0; j < 4; ++j) t = fmaxf(t, s[ct][sb][j]);
;             t = fmaxf(t, __shfl_xor(t, 16)); t = fmaxf(t, __shfl_xor(t, 32));
;             tz[ct] = t; un[ct] = st.m[ct] < -1e29f;
;             nd[ct] = (t > -1e29f) && (t > ATT_THR || un[ct]);
;         }
;         if (__builtin_amdgcn_ballot_w64(nd[0] || nd[1]) != 0ull) {
.LBB0_1171:
	s_and_b64 vcc, exec, s[0:1]
	s_cbranch_vccz .LBB0_1183
	ds_read_b128 v[60:63], v193
	ds_read_b128 v[64:67], v193 offset:64
	v_cmp_gt_f32_e64 s[4:5], s96, v189
	v_cmp_gt_f32_e64 s[0:1], s96, v190
	s_mov_b64 s[2:3], 0
	v_cndmask_b32_e64 v68, -v189, 0, s[4:5]
	v_cndmask_b32_e64 v92, -v190, 0, s[0:1]
	v_mov_b32_e32 v69, v68
	v_mov_b32_e32 v93, v92
	v_mov_b64_e32 v[70:71], v[68:69]
	v_mov_b64_e32 v[94:95], v[92:93]
	s_waitcnt lgkmcnt(1)
	v_mfma_f32_16x16x32_bf16 v[72:75], v[60:63], v[4:7], v[68:71]
	s_mov_b64 s[6:7], 0
	v_mfma_f32_16x16x32_bf16 v[60:63], v[60:63], v[12:15], v[92:95]
	s_waitcnt lgkmcnt(0)
	v_mfma_f32_16x16x32_bf16 v[80:83], v[64:67], v[8:11], v[72:75]
	v_mfma_f32_16x16x32_bf16 v[72:75], v[64:67], v[16:19], v[60:63]
	s_nop 4
	ds_read_b128 v[60:63], v193 offset:2304
	ds_read_b128 v[64:67], v193 offset:2368
	v_max3_f32 v3, v80, s36, v81
	v_max3_f32 v3, v3, v82, v83
	s_waitcnt lgkmcnt(1)
	v_mfma_f32_16x16x32_bf16 v[76:79], v[60:63], v[4:7], v[68:71]
	v_mfma_f32_16x16x32_bf16 v[60:63], v[60:63], v[12:15], v[92:95]
	s_waitcnt lgkmcnt(0)
	v_mfma_f32_16x16x32_bf16 v[84:87], v[64:67], v[8:11], v[76:79]
	v_mfma_f32_16x16x32_bf16 v[64:67], v[64:67], v[16:19], v[60:63]
	s_nop 4
	ds_read_b128 v[60:63], v193 offset:4608
	ds_read_b128 v[88:91], v193 offset:4672
	ds_read_b128 v[100:103], v193 offset:6912
	ds_read_b128 v[104:107], v193 offset:6976
	v_max3_f32 v3, v3, v84, v85
	s_waitcnt lgkmcnt(3)
	v_mfma_f32_16x16x32_bf16 v[76:79], v[60:63], v[4:7], v[68:71]
	v_max3_f32 v3, v3, v86, v87
	v_mfma_f32_16x16x32_bf16 v[60:63], v[60:63], v[12:15], v[92:95]
	s_waitcnt lgkmcnt(1)
	v_mfma_f32_16x16x32_bf16 v[68:71], v[100:103], v[4:7], v[68:71]
	v_mfma_f32_16x16x32_bf16 v[76:79], v[88:91], v[8:11], v[76:79]
	v_mfma_f32_16x16x32_bf16 v[60:63], v[88:91], v[16:19], v[60:63]
	s_waitcnt lgkmcnt(0)
	v_mfma_f32_16x16x32_bf16 v[88:91], v[104:107], v[8:11], v[68:71]
	s_nop 4
	v_max3_f32 v3, v3, v76, v77
	v_max3_f32 v3, v3, v78, v79
	v_mfma_f32_16x16x32_bf16 v[68:71], v[100:103], v[12:15], v[92:95]
	v_mfma_f32_16x16x32_bf16 v[68:71], v[104:107], v[16:19], v[68:71]
	v_max3_f32 v3, v3, v88, v89
	v_max3_f32 v3, v3, v90, v91
	ds_bpermute_b32 v92, v185, v3
	s_waitcnt lgkmcnt(0)
	v_max_f32_e32 v3, v3, v92
	ds_bpermute_b32 v92, v153, v3
	s_waitcnt lgkmcnt(0)
	v_max_f32_e32 v92, v3, v92
	v_cmp_lt_f32_e32 vcc, s96, v92
	s_and_saveexec_b64 s[8:9], vcc
	s_cbranch_execz .LBB0_1176
	v_cmp_nlt_f32_e32 vcc, s95, v92
	s_mov_b64 s[6:7], -1
	s_and_saveexec_b64 s[12:13], vcc
	s_orn2_b64 s[6:7], s[4:5], exec
	s_or_b64 exec, exec, s[12:13]
	s_and_b64 s[6:7], s[6:7], exec
